# wave_rstd reload blocks (ConvFused, SwiGLU x2): 8 serialized load-wait-reduce round trips -> 8 loads issued back to back, one wait
# baseline (speedup 1.0000x reference)
.LBB0_162:
	s_waitcnt lgkmcnt(0)
	v_mov_b32_e32 v132, v226
	v_and_b32_e32 v133, 64, v219
	v_ashrrev_i32_e32 v128, 31, v132
	v_lshrrev_b32_e32 v128, 30, v128
	v_add_u32_e32 v128, v132, v128
	v_ashrrev_i32_e32 v144, 2, v128
	v_and_b32_e32 v128, 0x3ffffffc, v128
	v_lshlrev_b32_e32 v130, 1, v144
	v_sub_u32_e32 v128, v132, v128
	v_and_b32_e32 v130, 0xffffff80, v130
	v_and_or_b32 v131, v144, 63, s42
	v_lshlrev_b32_e32 v128, 2, v128
	v_add_u32_e32 v130, v131, v130
	v_ashrrev_i32_e32 v129, 31, v128
	v_ashrrev_i32_e32 v131, 31, v130
	v_lshl_add_u64 v[128:129], v[128:129], 2, s[8:9]
	v_lshlrev_b64 v[134:135], 6, v[130:131]
	v_lshl_add_u64 v[134:135], v[128:129], 0, v[134:135]
	global_load_dwordx4 v[148:151], v[134:135], off offset:1024
	global_load_dwordx4 v[152:155], v[134:135], off offset:2048
	global_load_dwordx4 v[156:159], v[134:135], off offset:3072
	v_add_co_u32_e32 v250, vcc, 0x2000, v134
	v_addc_co_u32_e32 v251, vcc, 0, v135, vcc
	global_load_dwordx4 v[160:163], v[250:251], off
	global_load_dwordx4 v[164:167], v[250:251], off offset:1024
	global_load_dwordx4 v[168:171], v[250:251], off offset:2048
	global_load_dwordx4 v[172:175], v[250:251], off offset:3072
	global_load_dwordx4 v[134:137], v[134:135], off
	v_add_u32_e32 v138, 64, v133
	v_add_u32_e32 v130, 0x80, v130
	s_waitcnt vmcnt(0)
	v_add_f32_e32 v131, v134, v135
	v_add_f32_e32 v134, v136, v137
	v_add_f32_e32 v131, v131, v134
	v_xor_b32_e32 v134, 1, v219
	v_cmp_lt_i32_e32 vcc, v134, v138
	s_nop 1
	v_cndmask_b32_e32 v134, v219, v134, vcc
	v_lshlrev_b32_e32 v136, 2, v134
	ds_bpermute_b32 v134, v136, v131
	s_waitcnt lgkmcnt(0)
	v_add_f32_e32 v131, v131, v134
	v_xor_b32_e32 v134, 2, v219
	v_cmp_lt_i32_e32 vcc, v134, v138
	s_nop 1
	v_cndmask_b32_e32 v134, v219, v134, vcc
	v_lshlrev_b32_e32 v135, 2, v134
	ds_bpermute_b32 v134, v135, v131
	s_waitcnt lgkmcnt(0)
	v_add_f32_e32 v131, v131, v134
	v_fmamk_f32 v131, v131, 0x3a800000, v220
	v_rsq_f32_e32 v134, v131
	v_add_u32_e32 v131, 16, v144
	v_lshlrev_b32_e32 v137, 1, v131
	v_and_b32_e32 v137, 0xffffff80, v137
	v_and_or_b32 v131, v131, 63, s42
	v_add_u32_e32 v138, v131, v137
	v_ashrrev_i32_e32 v139, 31, v138
	v_lshlrev_b64 v[138:139], 6, v[138:139]
	v_lshl_add_u64 v[138:139], v[128:129], 0, v[138:139]
	s_waitcnt vmcnt(0)
	v_add_f32_e32 v131, v148, v149
	v_add_f32_e32 v137, v150, v151
	v_add_f32_e32 v131, v131, v137
	ds_bpermute_b32 v137, v136, v131
	s_waitcnt lgkmcnt(0)
	v_add_f32_e32 v131, v131, v137
	ds_bpermute_b32 v137, v135, v131
	s_waitcnt lgkmcnt(0)
	v_add_f32_e32 v131, v131, v137
	v_fmamk_f32 v131, v131, 0x3a800000, v220
	v_rsq_f32_e32 v137, v131
	v_add_u32_e32 v131, 32, v144
	v_lshlrev_b32_e32 v138, 1, v131
	v_and_b32_e32 v138, 0xffffff80, v138
	v_and_or_b32 v131, v131, 63, s42
	v_add_u32_e32 v138, v131, v138
	v_ashrrev_i32_e32 v139, 31, v138
	v_lshlrev_b64 v[138:139], 6, v[138:139]
	v_lshl_add_u64 v[138:139], v[128:129], 0, v[138:139]
	s_waitcnt vmcnt(0)
	v_add_f32_e32 v131, v152, v153
	v_add_f32_e32 v138, v154, v155
	v_add_f32_e32 v131, v131, v138
	ds_bpermute_b32 v138, v136, v131
	s_waitcnt lgkmcnt(0)
	v_add_f32_e32 v131, v131, v138
	ds_bpermute_b32 v138, v135, v131
	s_waitcnt lgkmcnt(0)
	v_add_f32_e32 v131, v131, v138
	v_fmamk_f32 v131, v131, 0x3a800000, v220
	v_rsq_f32_e32 v138, v131
	v_add_u32_e32 v131, 48, v144
	v_lshlrev_b32_e32 v139, 1, v131
	v_and_b32_e32 v139, 0xffffff80, v139
	v_and_or_b32 v131, v131, 63, s42
	v_add_u32_e32 v140, v131, v139
	v_ashrrev_i32_e32 v141, 31, v140
	v_lshlrev_b64 v[140:141], 6, v[140:141]
	v_lshl_add_u64 v[140:141], v[128:129], 0, v[140:141]
	s_waitcnt vmcnt(0)
	v_add_f32_e32 v131, v156, v157
	v_add_f32_e32 v139, v158, v159
	v_add_f32_e32 v131, v131, v139
	ds_bpermute_b32 v139, v136, v131
	s_waitcnt lgkmcnt(0)
	v_add_f32_e32 v131, v131, v139
	ds_bpermute_b32 v139, v135, v131
	s_waitcnt lgkmcnt(0)
	v_add_f32_e32 v131, v131, v139
	v_fmamk_f32 v131, v131, 0x3a800000, v220
	v_rsq_f32_e32 v139, v131
	v_ashrrev_i32_e32 v131, 31, v130
	v_lshlrev_b64 v[130:131], 6, v[130:131]
	v_lshl_add_u64 v[130:131], v[128:129], 0, v[130:131]
	s_waitcnt vmcnt(0)
	v_add_f32_e32 v130, v160, v161
	v_add_f32_e32 v131, v162, v163
	v_add_f32_e32 v130, v130, v131
	ds_bpermute_b32 v131, v136, v130
	s_waitcnt lgkmcnt(0)
	v_add_f32_e32 v130, v130, v131
	ds_bpermute_b32 v131, v135, v130
	s_waitcnt lgkmcnt(0)
	v_add_f32_e32 v130, v130, v131
	v_fmamk_f32 v130, v130, 0x3a800000, v220
	v_rsq_f32_e32 v145, v130
	v_add_u32_e32 v130, 0x50, v144
	v_lshlrev_b32_e32 v131, 1, v130
	v_and_b32_e32 v131, 0xffffff80, v131
	v_and_or_b32 v130, v130, 63, s42
	v_add_u32_e32 v130, v130, v131
	v_ashrrev_i32_e32 v131, 31, v130
	v_lshlrev_b64 v[130:131], 6, v[130:131]
	v_lshl_add_u64 v[130:131], v[128:129], 0, v[130:131]
	s_waitcnt vmcnt(0)
	v_add_f32_e32 v130, v164, v165
	v_add_f32_e32 v131, v166, v167
	v_add_f32_e32 v130, v130, v131
	ds_bpermute_b32 v131, v136, v130
	s_waitcnt lgkmcnt(0)
	v_add_f32_e32 v130, v130, v131
	ds_bpermute_b32 v131, v135, v130
	s_waitcnt lgkmcnt(0)
	v_add_f32_e32 v130, v130, v131
	v_fmamk_f32 v130, v130, 0x3a800000, v220
	v_rsq_f32_e32 v146, v130
	v_add_u32_e32 v130, 0x60, v144
	v_lshlrev_b32_e32 v131, 1, v130
	v_and_b32_e32 v131, 0xffffff80, v131
	v_and_or_b32 v130, v130, 63, s42
	v_add_u32_e32 v130, v130, v131
	v_ashrrev_i32_e32 v131, 31, v130
	v_lshlrev_b64 v[130:131], 6, v[130:131]
	v_lshl_add_u64 v[130:131], v[128:129], 0, v[130:131]
	s_waitcnt vmcnt(0)
	v_add_f32_e32 v130, v168, v169
	v_add_f32_e32 v131, v170, v171
	v_add_f32_e32 v130, v130, v131
	ds_bpermute_b32 v131, v136, v130
	s_waitcnt lgkmcnt(0)
	v_add_f32_e32 v130, v130, v131
	ds_bpermute_b32 v131, v135, v130
	s_waitcnt lgkmcnt(0)
	v_add_f32_e32 v130, v130, v131
	v_fmamk_f32 v130, v130, 0x3a800000, v220
	v_rsq_f32_e32 v140, v130
	v_add_u32_e32 v130, 0x70, v144
	v_lshlrev_b32_e32 v131, 1, v130
	v_and_b32_e32 v131, 0xffffff80, v131
	v_and_or_b32 v130, v130, 63, s42
	v_add_u32_e32 v130, v130, v131
	v_ashrrev_i32_e32 v131, 31, v130
	v_lshlrev_b64 v[130:131], 6, v[130:131]
	v_lshl_add_u64 v[128:129], v[128:129], 0, v[130:131]
	s_waitcnt vmcnt(0)
	v_add_f32_e32 v128, v172, v173
	v_add_f32_e32 v129, v174, v175
	v_add_f32_e32 v128, v128, v129
	ds_bpermute_b32 v129, v136, v128
	s_waitcnt lgkmcnt(0)
	v_add_f32_e32 v128, v128, v129
	ds_bpermute_b32 v129, v135, v128
	s_waitcnt lgkmcnt(0)
	v_add_f32_e32 v128, v128, v129
	v_fmamk_f32 v128, v128, 0x3a800000, v220
	v_rsq_f32_e32 v135, v128
	v_lshlrev_b32_e32 v128, 2, v132
	v_and_or_b32 v128, v128, 60, v133
	v_lshlrev_b32_e32 v136, 2, v128
	ds_bpermute_b32 v128, v136, v134
	ds_bpermute_b32 v129, v136, v137
	ds_bpermute_b32 v130, v136, v138
	ds_bpermute_b32 v131, v136, v139
	ds_bpermute_b32 v132, v136, v145
	ds_bpermute_b32 v133, v136, v146
	ds_bpermute_b32 v134, v136, v140
	ds_bpermute_b32 v135, v136, v135
	s_and_saveexec_b64 s[10:11], s[38:39]
	s_cbranch_execz .LBB0_164
	s_waitcnt lgkmcnt(6)
	ds_write2_b32 v227, v128, v129 offset1:16
	s_waitcnt lgkmcnt(5)
	ds_write2_b32 v227, v130, v131 offset0:32 offset1:48
	s_waitcnt lgkmcnt(4)
	ds_write2_b32 v227, v132, v133 offset0:64 offset1:80
	s_waitcnt lgkmcnt(3)
	ds_write2_b32 v227, v134, v135 offset0:96 offset1:112

.LBB0_397:
	s_lshl_b32 s10, s68, 8
	s_add_i32 s10, s10, s58
	s_cmp_eq_u32 s68, s69
	s_cbranch_scc1 .LBB0_401
	v_mov_b32_e32 v142, v152
	v_and_b32_e32 v143, 64, v219
	v_ashrrev_i32_e32 v128, 31, v142
	v_lshrrev_b32_e32 v128, 30, v128
	v_add_u32_e32 v128, v142, v128
	v_ashrrev_i32_e32 v160, 2, v128
	v_and_b32_e32 v128, 0x3ffffffc, v128
	v_lshlrev_b32_e32 v130, 1, v160
	v_sub_u32_e32 v128, v142, v128
	v_and_b32_e32 v130, 0xffffff80, v130
	v_and_or_b32 v131, v160, 63, s10
	v_lshlrev_b32_e32 v128, 2, v128
	v_add_u32_e32 v130, v131, v130
	v_ashrrev_i32_e32 v129, 31, v128
	v_ashrrev_i32_e32 v131, 31, v130
	v_lshl_add_u64 v[128:129], v[128:129], 2, s[0:1]
	v_lshlrev_b64 v[144:145], 6, v[130:131]
	v_lshl_add_u64 v[144:145], v[128:129], 0, v[144:145]
	global_load_dwordx4 v[164:167], v[144:145], off offset:1024
	global_load_dwordx4 v[168:171], v[144:145], off offset:2048
	global_load_dwordx4 v[172:175], v[144:145], off offset:3072
	v_add_co_u32_e32 v250, vcc, 0x2000, v144
	v_addc_co_u32_e32 v251, vcc, 0, v145, vcc
	global_load_dwordx4 v[186:189], v[250:251], off
	global_load_dwordx4 v[190:193], v[250:251], off offset:1024
	global_load_dwordx4 v[194:197], v[250:251], off offset:2048
	global_load_dwordx4 v[198:201], v[250:251], off offset:3072
	global_load_dwordx4 v[144:147], v[144:145], off
	v_add_u32_e32 v148, 64, v143
	v_add_u32_e32 v130, 0x80, v130
	s_waitcnt vmcnt(0)
	v_add_f32_e32 v131, v144, v145
	v_add_f32_e32 v144, v146, v147
	v_add_f32_e32 v131, v131, v144
	v_xor_b32_e32 v144, 1, v219
	v_cmp_lt_i32_e32 vcc, v144, v148
	s_nop 1
	v_cndmask_b32_e32 v144, v219, v144, vcc
	v_lshlrev_b32_e32 v146, 2, v144
	ds_bpermute_b32 v144, v146, v131
	s_waitcnt lgkmcnt(0)
	v_add_f32_e32 v131, v131, v144
	v_xor_b32_e32 v144, 2, v219
	v_cmp_lt_i32_e32 vcc, v144, v148
	s_nop 1
	v_cndmask_b32_e32 v144, v219, v144, vcc
	v_lshlrev_b32_e32 v145, 2, v144
	ds_bpermute_b32 v144, v145, v131
	s_waitcnt lgkmcnt(0)
	v_add_f32_e32 v131, v131, v144
	v_fmamk_f32 v131, v131, 0x3a800000, v220
	v_rsq_f32_e32 v144, v131
	v_add_u32_e32 v131, 16, v160
	v_lshlrev_b32_e32 v147, 1, v131
	v_and_b32_e32 v147, 0xffffff80, v147
	v_and_or_b32 v131, v131, 63, s10
	v_add_u32_e32 v148, v131, v147
	v_ashrrev_i32_e32 v149, 31, v148
	v_lshlrev_b64 v[148:149], 6, v[148:149]
	v_lshl_add_u64 v[148:149], v[128:129], 0, v[148:149]
	s_waitcnt vmcnt(0)
	v_add_f32_e32 v131, v164, v165
	v_add_f32_e32 v147, v166, v167
	v_add_f32_e32 v131, v131, v147
	ds_bpermute_b32 v147, v146, v131
	s_waitcnt lgkmcnt(0)
	v_add_f32_e32 v131, v131, v147
	ds_bpermute_b32 v147, v145, v131
	s_waitcnt lgkmcnt(0)
	v_add_f32_e32 v131, v131, v147
	v_fmamk_f32 v131, v131, 0x3a800000, v220
	v_rsq_f32_e32 v147, v131
	v_add_u32_e32 v131, 32, v160
	v_lshlrev_b32_e32 v148, 1, v131
	v_and_b32_e32 v148, 0xffffff80, v148
	v_and_or_b32 v131, v131, 63, s10
	v_add_u32_e32 v148, v131, v148
	v_ashrrev_i32_e32 v149, 31, v148
	v_lshlrev_b64 v[148:149], 6, v[148:149]
	v_lshl_add_u64 v[148:149], v[128:129], 0, v[148:149]
	s_waitcnt vmcnt(0)
	v_add_f32_e32 v131, v168, v169
	v_add_f32_e32 v148, v170, v171
	v_add_f32_e32 v131, v131, v148
	ds_bpermute_b32 v148, v146, v131
	s_waitcnt lgkmcnt(0)
	v_add_f32_e32 v131, v131, v148
	ds_bpermute_b32 v148, v145, v131
	s_waitcnt lgkmcnt(0)
	v_add_f32_e32 v131, v131, v148
	v_fmamk_f32 v131, v131, 0x3a800000, v220
	v_rsq_f32_e32 v148, v131
	v_add_u32_e32 v131, 48, v160
	v_lshlrev_b32_e32 v149, 1, v131
	v_and_b32_e32 v149, 0xffffff80, v149
	v_and_or_b32 v131, v131, 63, s10
	v_add_u32_e32 v156, v131, v149
	v_ashrrev_i32_e32 v157, 31, v156
	v_lshlrev_b64 v[156:157], 6, v[156:157]
	v_lshl_add_u64 v[156:157], v[128:129], 0, v[156:157]
	s_waitcnt vmcnt(0)
	v_add_f32_e32 v131, v172, v173
	v_add_f32_e32 v149, v174, v175
	v_add_f32_e32 v131, v131, v149
	ds_bpermute_b32 v149, v146, v131
	s_waitcnt lgkmcnt(0)
	v_add_f32_e32 v131, v131, v149
	ds_bpermute_b32 v149, v145, v131
	s_waitcnt lgkmcnt(0)
	v_add_f32_e32 v131, v131, v149
	v_fmamk_f32 v131, v131, 0x3a800000, v220
	v_rsq_f32_e32 v149, v131
	v_ashrrev_i32_e32 v131, 31, v130
	v_lshlrev_b64 v[130:131], 6, v[130:131]
	v_lshl_add_u64 v[130:131], v[128:129], 0, v[130:131]
	s_waitcnt vmcnt(0)
	v_add_f32_e32 v130, v186, v187
	v_add_f32_e32 v131, v188, v189
	v_add_f32_e32 v130, v130, v131
	ds_bpermute_b32 v131, v146, v130
	s_waitcnt lgkmcnt(0)
	v_add_f32_e32 v130, v130, v131
	ds_bpermute_b32 v131, v145, v130
	s_waitcnt lgkmcnt(0)
	v_add_f32_e32 v130, v130, v131
	v_fmamk_f32 v130, v130, 0x3a800000, v220
	v_rsq_f32_e32 v161, v130
	v_add_u32_e32 v130, 0x50, v160
	v_lshlrev_b32_e32 v131, 1, v130
	v_and_b32_e32 v131, 0xffffff80, v131
	v_and_or_b32 v130, v130, 63, s10
	v_add_u32_e32 v130, v130, v131
	v_ashrrev_i32_e32 v131, 31, v130
	v_lshlrev_b64 v[130:131], 6, v[130:131]
	v_lshl_add_u64 v[130:131], v[128:129], 0, v[130:131]
	s_waitcnt vmcnt(0)
	v_add_f32_e32 v130, v190, v191
	v_add_f32_e32 v131, v192, v193
	v_add_f32_e32 v130, v130, v131
	ds_bpermute_b32 v131, v146, v130
	s_waitcnt lgkmcnt(0)
	v_add_f32_e32 v130, v130, v131
	ds_bpermute_b32 v131, v145, v130
	s_waitcnt lgkmcnt(0)
	v_add_f32_e32 v130, v130, v131
	v_fmamk_f32 v130, v130, 0x3a800000, v220
	v_rsq_f32_e32 v162, v130
	v_add_u32_e32 v130, 0x60, v160
	v_lshlrev_b32_e32 v131, 1, v130
	v_and_b32_e32 v131, 0xffffff80, v131
	v_and_or_b32 v130, v130, 63, s10
	v_add_u32_e32 v130, v130, v131
	v_ashrrev_i32_e32 v131, 31, v130
	v_lshlrev_b64 v[130:131], 6, v[130:131]
	v_lshl_add_u64 v[130:131], v[128:129], 0, v[130:131]
	s_waitcnt vmcnt(0)
	v_add_f32_e32 v130, v194, v195
	v_add_f32_e32 v131, v196, v197
	v_add_f32_e32 v130, v130, v131
	ds_bpermute_b32 v131, v146, v130
	s_waitcnt lgkmcnt(0)
	v_add_f32_e32 v130, v130, v131
	ds_bpermute_b32 v131, v145, v130
	s_waitcnt lgkmcnt(0)
	v_add_f32_e32 v130, v130, v131
	v_fmamk_f32 v130, v130, 0x3a800000, v220
	v_rsq_f32_e32 v156, v130
	v_add_u32_e32 v130, 0x70, v160
	v_lshlrev_b32_e32 v131, 1, v130
	v_and_b32_e32 v131, 0xffffff80, v131
	v_and_or_b32 v130, v130, 63, s10
	v_add_u32_e32 v130, v130, v131
	v_ashrrev_i32_e32 v131, 31, v130
	v_lshlrev_b64 v[130:131], 6, v[130:131]
	v_lshl_add_u64 v[128:129], v[128:129], 0, v[130:131]
	s_waitcnt vmcnt(0)
	v_add_f32_e32 v128, v198, v199
	v_add_f32_e32 v129, v200, v201
	v_add_f32_e32 v128, v128, v129
	ds_bpermute_b32 v129, v146, v128
	s_waitcnt lgkmcnt(0)
	v_add_f32_e32 v128, v128, v129
	ds_bpermute_b32 v129, v145, v128
	s_waitcnt lgkmcnt(0)
	v_add_f32_e32 v128, v128, v129
	v_fmamk_f32 v128, v128, 0x3a800000, v220
	v_rsq_f32_e32 v128, v128
	v_lshlrev_b32_e32 v129, 2, v142
	v_and_or_b32 v129, v129, 60, v143
	v_lshlrev_b32_e32 v146, 2, v129
	ds_bpermute_b32 v145, v146, v144
	ds_bpermute_b32 v144, v146, v147
	ds_bpermute_b32 v143, v146, v148
	ds_bpermute_b32 v142, v146, v149
	ds_bpermute_b32 v131, v146, v161
	ds_bpermute_b32 v130, v146, v162
	ds_bpermute_b32 v129, v146, v156
	ds_bpermute_b32 v128, v146, v128
	s_and_saveexec_b64 s[28:29], s[40:41]
	s_cbranch_execz .LBB0_400
	s_waitcnt lgkmcnt(7)
	v_mul_f32_e32 v146, 0xbfb8aa3b, v145
	v_mul_f32_e32 v145, v145, v145
	s_waitcnt lgkmcnt(6)
	v_mul_f32_e32 v147, 0xbfb8aa3b, v144
	v_mul_f32_e32 v144, v144, v144
	v_rcp_f32_e32 v145, v145
	v_rcp_f32_e32 v144, v144
	ds_write2_b32 v153, v146, v147 offset1:16
	v_add_u32_e32 v146, 0x1000, v153
	ds_write2_b32 v146, v145, v144 offset1:16
	s_waitcnt lgkmcnt(7)
	v_mul_f32_e32 v144, 0xbfb8aa3b, v143
	v_mul_f32_e32 v143, v143, v143
	s_waitcnt lgkmcnt(6)
	v_mul_f32_e32 v145, 0xbfb8aa3b, v142
	v_mul_f32_e32 v142, v142, v142
	v_rcp_f32_e32 v143, v143
	v_rcp_f32_e32 v142, v142
	ds_write2_b32 v153, v144, v145 offset0:32 offset1:48
	ds_write2_b32 v146, v143, v142 offset0:32 offset1:48
	s_waitcnt lgkmcnt(7)
	v_mul_f32_e32 v142, 0xbfb8aa3b, v131
	v_mul_f32_e32 v131, v131, v131
	s_waitcnt lgkmcnt(6)
	v_mul_f32_e32 v143, 0xbfb8aa3b, v130
	v_mul_f32_e32 v130, v130, v130
	v_rcp_f32_e32 v131, v131
	v_rcp_f32_e32 v130, v130
	ds_write2_b32 v153, v142, v143 offset0:64 offset1:80
	ds_write2_b32 v146, v131, v130 offset0:64 offset1:80
	s_waitcnt lgkmcnt(7)
	v_mul_f32_e32 v130, 0xbfb8aa3b, v129
	v_mul_f32_e32 v129, v129, v129
	s_waitcnt lgkmcnt(6)
	v_mul_f32_e32 v131, 0xbfb8aa3b, v128
	v_mul_f32_e32 v128, v128, v128
	v_rcp_f32_e32 v129, v129
	v_rcp_f32_e32 v128, v128
	ds_write2_b32 v153, v130, v131 offset0:96 offset1:112
	ds_write2_b32 v146, v129, v128 offset0:96 offset1:112

.LBB0_1147:
	v_mov_b32_e32 v142, v152
	v_and_b32_e32 v143, 64, v219
	v_ashrrev_i32_e32 v128, 31, v142
	v_lshrrev_b32_e32 v128, 30, v128
	v_add_u32_e32 v128, v142, v128
	s_waitcnt vmcnt(0)
	v_ashrrev_i32_e32 v160, 2, v128
	v_and_b32_e32 v128, 0x3ffffffc, v128
	v_lshlrev_b32_e32 v130, 1, v160
	v_sub_u32_e32 v128, v142, v128
	v_and_b32_e32 v130, 0xffffff80, v130
	v_and_or_b32 v131, v160, 63, s10
	v_lshlrev_b32_e32 v128, 2, v128
	v_add_u32_e32 v130, v131, v130
	v_ashrrev_i32_e32 v129, 31, v128
	v_ashrrev_i32_e32 v131, 31, v130
	v_lshl_add_u64 v[128:129], v[128:129], 2, s[0:1]
	v_lshlrev_b64 v[144:145], 6, v[130:131]
	v_lshl_add_u64 v[144:145], v[128:129], 0, v[144:145]
	global_load_dwordx4 v[164:167], v[144:145], off offset:1024
	global_load_dwordx4 v[168:171], v[144:145], off offset:2048
	global_load_dwordx4 v[172:175], v[144:145], off offset:3072
	v_add_co_u32_e32 v198, vcc, 0x2000, v144
	v_addc_co_u32_e32 v199, vcc, 0, v145, vcc
	global_load_dwordx4 v[176:179], v[198:199], off
	global_load_dwordx4 v[194:197], v[198:199], off offset:1024
	global_load_dwordx4 v[206:209], v[198:199], off offset:2048
	global_load_dwordx4 v[210:213], v[198:199], off offset:3072
	global_load_dwordx4 v[144:147], v[144:145], off
	v_add_u32_e32 v148, 64, v143
	v_add_u32_e32 v130, 0x80, v130
	s_waitcnt vmcnt(0)
	v_add_f32_e32 v131, v144, v145
	v_add_f32_e32 v144, v146, v147
	v_add_f32_e32 v131, v131, v144
	v_xor_b32_e32 v144, 1, v219
	v_cmp_lt_i32_e32 vcc, v144, v148
	s_nop 1
	v_cndmask_b32_e32 v144, v219, v144, vcc
	v_lshlrev_b32_e32 v146, 2, v144
	ds_bpermute_b32 v144, v146, v131
	s_waitcnt lgkmcnt(0)
	v_add_f32_e32 v131, v131, v144
	v_xor_b32_e32 v144, 2, v219
	v_cmp_lt_i32_e32 vcc, v144, v148
	s_nop 1
	v_cndmask_b32_e32 v144, v219, v144, vcc
	v_lshlrev_b32_e32 v145, 2, v144
	ds_bpermute_b32 v144, v145, v131
	s_waitcnt lgkmcnt(0)
	v_add_f32_e32 v131, v131, v144
	v_fmamk_f32 v131, v131, 0x3a800000, v200
	v_rsq_f32_e32 v144, v131
	v_add_u32_e32 v131, 16, v160
	v_lshlrev_b32_e32 v147, 1, v131
	v_and_b32_e32 v147, 0xffffff80, v147
	v_and_or_b32 v131, v131, 63, s10
	v_add_u32_e32 v148, v131, v147
	v_ashrrev_i32_e32 v149, 31, v148
	v_lshlrev_b64 v[148:149], 6, v[148:149]
	v_lshl_add_u64 v[148:149], v[128:129], 0, v[148:149]
	s_waitcnt vmcnt(0)
	v_add_f32_e32 v131, v164, v165
	v_add_f32_e32 v147, v166, v167
	v_add_f32_e32 v131, v131, v147
	ds_bpermute_b32 v147, v146, v131
	s_waitcnt lgkmcnt(0)
	v_add_f32_e32 v131, v131, v147
	ds_bpermute_b32 v147, v145, v131
	s_waitcnt lgkmcnt(0)
	v_add_f32_e32 v131, v131, v147
	v_fmamk_f32 v131, v131, 0x3a800000, v200
	v_rsq_f32_e32 v147, v131
	v_add_u32_e32 v131, 32, v160
	v_lshlrev_b32_e32 v148, 1, v131
	v_and_b32_e32 v148, 0xffffff80, v148
	v_and_or_b32 v131, v131, 63, s10
	v_add_u32_e32 v148, v131, v148
	v_ashrrev_i32_e32 v149, 31, v148
	v_lshlrev_b64 v[148:149], 6, v[148:149]
	v_lshl_add_u64 v[148:149], v[128:129], 0, v[148:149]
	s_waitcnt vmcnt(0)
	v_add_f32_e32 v131, v168, v169
	v_add_f32_e32 v148, v170, v171
	v_add_f32_e32 v131, v131, v148
	ds_bpermute_b32 v148, v146, v131
	s_waitcnt lgkmcnt(0)
	v_add_f32_e32 v131, v131, v148
	ds_bpermute_b32 v148, v145, v131
	s_waitcnt lgkmcnt(0)
	v_add_f32_e32 v131, v131, v148
	v_fmamk_f32 v131, v131, 0x3a800000, v200
	v_rsq_f32_e32 v148, v131
	v_add_u32_e32 v131, 48, v160
	v_lshlrev_b32_e32 v149, 1, v131
	v_and_b32_e32 v149, 0xffffff80, v149
	v_and_or_b32 v131, v131, 63, s10
	v_add_u32_e32 v156, v131, v149
	v_ashrrev_i32_e32 v157, 31, v156
	v_lshlrev_b64 v[156:157], 6, v[156:157]
	v_lshl_add_u64 v[156:157], v[128:129], 0, v[156:157]
	s_waitcnt vmcnt(0)
	v_add_f32_e32 v131, v172, v173
	v_add_f32_e32 v149, v174, v175
	v_add_f32_e32 v131, v131, v149
	ds_bpermute_b32 v149, v146, v131
	s_waitcnt lgkmcnt(0)
	v_add_f32_e32 v131, v131, v149
	ds_bpermute_b32 v149, v145, v131
	s_waitcnt lgkmcnt(0)
	v_add_f32_e32 v131, v131, v149
	v_fmamk_f32 v131, v131, 0x3a800000, v200
	v_rsq_f32_e32 v149, v131
	v_ashrrev_i32_e32 v131, 31, v130
	v_lshlrev_b64 v[130:131], 6, v[130:131]
	v_lshl_add_u64 v[130:131], v[128:129], 0, v[130:131]
	s_waitcnt vmcnt(0)
	v_add_f32_e32 v130, v176, v177
	v_add_f32_e32 v131, v178, v179
	v_add_f32_e32 v130, v130, v131
	ds_bpermute_b32 v131, v146, v130
	s_waitcnt lgkmcnt(0)
	v_add_f32_e32 v130, v130, v131
	ds_bpermute_b32 v131, v145, v130
	s_waitcnt lgkmcnt(0)
	v_add_f32_e32 v130, v130, v131
	v_fmamk_f32 v130, v130, 0x3a800000, v200
	v_rsq_f32_e32 v161, v130
	v_add_u32_e32 v130, 0x50, v160
	v_lshlrev_b32_e32 v131, 1, v130
	v_and_b32_e32 v131, 0xffffff80, v131
	v_and_or_b32 v130, v130, 63, s10
	v_add_u32_e32 v130, v130, v131
	v_ashrrev_i32_e32 v131, 31, v130
	v_lshlrev_b64 v[130:131], 6, v[130:131]
	v_lshl_add_u64 v[130:131], v[128:129], 0, v[130:131]
	s_waitcnt vmcnt(0)
	v_add_f32_e32 v130, v194, v195
	v_add_f32_e32 v131, v196, v197
	v_add_f32_e32 v130, v130, v131
	ds_bpermute_b32 v131, v146, v130
	s_waitcnt lgkmcnt(0)
	v_add_f32_e32 v130, v130, v131
	ds_bpermute_b32 v131, v145, v130
	s_waitcnt lgkmcnt(0)
	v_add_f32_e32 v130, v130, v131
	v_fmamk_f32 v130, v130, 0x3a800000, v200
	v_rsq_f32_e32 v162, v130
	v_add_u32_e32 v130, 0x60, v160
	v_lshlrev_b32_e32 v131, 1, v130
	v_and_b32_e32 v131, 0xffffff80, v131
	v_and_or_b32 v130, v130, 63, s10
	v_add_u32_e32 v130, v130, v131
	v_ashrrev_i32_e32 v131, 31, v130
	v_lshlrev_b64 v[130:131], 6, v[130:131]
	v_lshl_add_u64 v[130:131], v[128:129], 0, v[130:131]
	s_waitcnt vmcnt(0)
	v_add_f32_e32 v130, v206, v207
	v_add_f32_e32 v131, v208, v209
	v_add_f32_e32 v130, v130, v131
	ds_bpermute_b32 v131, v146, v130
	s_waitcnt lgkmcnt(0)
	v_add_f32_e32 v130, v130, v131
	ds_bpermute_b32 v131, v145, v130
	s_waitcnt lgkmcnt(0)
	v_add_f32_e32 v130, v130, v131
	v_fmamk_f32 v130, v130, 0x3a800000, v200
	v_rsq_f32_e32 v156, v130
	v_add_u32_e32 v130, 0x70, v160
	v_lshlrev_b32_e32 v131, 1, v130
	v_and_b32_e32 v131, 0xffffff80, v131
	v_and_or_b32 v130, v130, 63, s10
	v_add_u32_e32 v130, v130, v131
	v_ashrrev_i32_e32 v131, 31, v130
	v_lshlrev_b64 v[130:131], 6, v[130:131]
	v_lshl_add_u64 v[128:129], v[128:129], 0, v[130:131]
	s_waitcnt vmcnt(0)
	v_add_f32_e32 v128, v210, v211
	v_add_f32_e32 v129, v212, v213
	v_add_f32_e32 v128, v128, v129
	ds_bpermute_b32 v129, v146, v128
	s_waitcnt lgkmcnt(0)
	v_add_f32_e32 v128, v128, v129
	ds_bpermute_b32 v129, v145, v128
	s_waitcnt lgkmcnt(0)
	v_add_f32_e32 v128, v128, v129
	v_fmamk_f32 v128, v128, 0x3a800000, v200
	v_rsq_f32_e32 v128, v128
	v_lshlrev_b32_e32 v129, 2, v142
	v_and_or_b32 v129, v129, 60, v143
	v_lshlrev_b32_e32 v146, 2, v129
	ds_bpermute_b32 v145, v146, v144
	ds_bpermute_b32 v144, v146, v147
	ds_bpermute_b32 v143, v146, v148
	ds_bpermute_b32 v142, v146, v149
	ds_bpermute_b32 v131, v146, v161
	ds_bpermute_b32 v130, v146, v162
	ds_bpermute_b32 v129, v146, v156
	ds_bpermute_b32 v128, v146, v128
	s_and_saveexec_b64 s[16:17], s[40:41]
	s_cbranch_execz .LBB0_1149
	s_waitcnt lgkmcnt(7)
	v_mul_f32_e32 v146, 0xbfb8aa3b, v145
	v_mul_f32_e32 v145, v145, v145
	s_waitcnt lgkmcnt(6)
	v_mul_f32_e32 v147, 0xbfb8aa3b, v144
	v_mul_f32_e32 v144, v144, v144
	v_rcp_f32_e32 v145, v145
	v_rcp_f32_e32 v144, v144
	ds_write2_b32 v153, v146, v147 offset1:16
	v_add_u32_e32 v146, 0x1000, v153
	ds_write2_b32 v146, v145, v144 offset1:16
	s_waitcnt lgkmcnt(7)
	v_mul_f32_e32 v144, 0xbfb8aa3b, v143
	v_mul_f32_e32 v143, v143, v143
	s_waitcnt lgkmcnt(6)
	v_mul_f32_e32 v145, 0xbfb8aa3b, v142
	v_mul_f32_e32 v142, v142, v142
	v_rcp_f32_e32 v143, v143
	v_rcp_f32_e32 v142, v142
	ds_write2_b32 v153, v144, v145 offset0:32 offset1:48
	ds_write2_b32 v146, v143, v142 offset0:32 offset1:48
	s_waitcnt lgkmcnt(7)
	v_mul_f32_e32 v142, 0xbfb8aa3b, v131
	v_mul_f32_e32 v131, v131, v131
	s_waitcnt lgkmcnt(6)
	v_mul_f32_e32 v143, 0xbfb8aa3b, v130
	v_mul_f32_e32 v130, v130, v130
	v_rcp_f32_e32 v131, v131
	v_rcp_f32_e32 v130, v130
	ds_write2_b32 v153, v142, v143 offset0:64 offset1:80
	ds_write2_b32 v146, v131, v130 offset0:64 offset1:80
	s_waitcnt lgkmcnt(7)
	v_mul_f32_e32 v130, 0xbfb8aa3b, v129
	v_mul_f32_e32 v129, v129, v129
	s_waitcnt lgkmcnt(6)
	v_mul_f32_e32 v131, 0xbfb8aa3b, v128
	v_mul_f32_e32 v128, v128, v128
	v_rcp_f32_e32 v129, v129
	v_rcp_f32_e32 v128, v128
	ds_write2_b32 v153, v130, v131 offset0:96 offset1:112
	ds_write2_b32 v146, v129, v128 offset0:96 offset1:112
